# attention unit epilogue: exchange-add loop de-serialised (two 4-deep LDS read buffers instead of read-wait-add x32)
# speedup vs baseline: 1.0052x; 1.0000x over previous
.LBB0_357:
	v_readlane_b32 s4, v254, 27
	v_lshlrev_b32_e32 v0, 4, v217
	s_waitcnt vmcnt(0) lgkmcnt(0)
	s_barrier
	s_nop 0
	v_add_u32_e32 v164, s4, v218
	s_lshl_b64 s[4:5], s[82:83], 1
	v_add_u32_e32 v2, s3, v164
	s_add_u32 s6, s48, s4
	s_addc_u32 s7, s49, s5
	v_ashrrev_i32_e32 v3, 31, v2
	v_lshl_add_u64 v[4:5], s[6:7], 0, v[0:1]
	v_lshlrev_b64 v[34:35], 13, v[2:3]
	v_lshl_add_u64 v[2:3], v[4:5], 0, v[34:35]
	s_movk_i32 s6, 0x4000
	v_add_co_u32_e32 v4, vcc, s6, v2
	s_mov_b32 s6, 0x8000
	s_nop 0
	v_addc_co_u32_e32 v5, vcc, 0, v3, vcc
	global_load_dwordx4 v[30:33], v[2:3], off
	global_load_dwordx4 v[26:29], v[4:5], off
	v_add_co_u32_e32 v4, vcc, s6, v2
	s_mov_b32 s6, 0x10000
	s_nop 0
	v_addc_co_u32_e32 v5, vcc, 0, v3, vcc
	v_add_co_u32_e32 v6, vcc, 0xc000, v2
	s_nop 1
	v_addc_co_u32_e32 v7, vcc, 0, v3, vcc
	global_load_dwordx4 v[22:25], v[4:5], off
	global_load_dwordx4 v[18:21], v[6:7], off
	v_add_co_u32_e32 v4, vcc, s6, v2
	s_nop 1
	v_addc_co_u32_e32 v5, vcc, 0, v3, vcc
	v_add_co_u32_e32 v6, vcc, 0x14000, v2
	s_nop 1
	v_addc_co_u32_e32 v7, vcc, 0, v3, vcc
	global_load_dwordx4 v[14:17], v[4:5], off
	global_load_dwordx4 v[10:13], v[6:7], off
	v_add_co_u32_e32 v4, vcc, 0x18000, v2
	s_nop 1
	v_addc_co_u32_e32 v5, vcc, 0, v3, vcc
	v_add_co_u32_e32 v2, vcc, 0x1c000, v2
	s_nop 1
	v_addc_co_u32_e32 v3, vcc, 0, v3, vcc
	global_load_dwordx4 v[6:9], v[4:5], off
	s_nop 0
	global_load_dwordx4 v[2:5], v[2:3], off
	s_andn2_b64 vcc, exec, s[0:1]
	s_cbranch_vccnz .LBB0_256
	ds_read_b128 v[190:193], v167
	ds_read_b128 v[194:197], v167 offset:1024
	ds_read_b128 v[198:201], v167 offset:2048
	ds_read_b128 v[202:205], v167 offset:3072
	ds_read_b128 v[234:237], v167 offset:4096
	ds_read_b128 v[238:241], v167 offset:5120
	ds_read_b128 v[242:245], v167 offset:6144
	ds_read_b128 v[246:249], v167 offset:7168
	s_waitcnt lgkmcnt(7)
	v_add_f32_e32 v165, v160, v190
	v_add_f32_e32 v161, v161, v191
	v_add_f32_e32 v160, v162, v192
	v_add_f32_e32 v0, v163, v193
	s_waitcnt lgkmcnt(6)
	v_add_f32_e32 v163, v156, v194
	v_add_f32_e32 v162, v157, v195
	v_add_f32_e32 v157, v158, v196
	v_add_f32_e32 v156, v159, v197
	s_waitcnt lgkmcnt(5)
	v_add_f32_e32 v159, v152, v198
	v_add_f32_e32 v158, v153, v199
	v_add_f32_e32 v153, v154, v200
	v_add_f32_e32 v152, v155, v201
	s_waitcnt lgkmcnt(4)
	v_add_f32_e32 v155, v148, v202
	v_add_f32_e32 v154, v149, v203
	v_add_f32_e32 v150, v150, v204
	v_add_f32_e32 v149, v151, v205
	ds_read_b128 v[190:193], v167 offset:8192
	ds_read_b128 v[194:197], v167 offset:9216
	ds_read_b128 v[198:201], v167 offset:10240
	ds_read_b128 v[202:205], v167 offset:11264
	s_waitcnt lgkmcnt(7)
	v_add_f32_e32 v151, v144, v234
	v_add_f32_e32 v148, v145, v235
	v_add_f32_e32 v145, v146, v236
	v_add_f32_e32 v144, v147, v237
	s_waitcnt lgkmcnt(6)
	v_add_f32_e32 v147, v140, v238
	v_add_f32_e32 v146, v141, v239
	v_add_f32_e32 v141, v142, v240
	v_add_f32_e32 v140, v143, v241
	s_waitcnt lgkmcnt(5)
	v_add_f32_e32 v143, v136, v242
	v_add_f32_e32 v142, v137, v243
	v_add_f32_e32 v137, v138, v244
	v_add_f32_e32 v136, v139, v245
	s_waitcnt lgkmcnt(4)
	v_add_f32_e32 v166, v132, v246
	v_add_f32_e32 v139, v133, v247
	v_add_f32_e32 v138, v134, v248
	v_add_f32_e32 v134, v135, v249
	ds_read_b128 v[234:237], v167 offset:12288
	ds_read_b128 v[238:241], v167 offset:13312
	ds_read_b128 v[242:245], v167 offset:14336
	ds_read_b128 v[246:249], v167 offset:15360
	s_waitcnt lgkmcnt(7)
	v_add_f32_e32 v133, v128, v190
	v_add_f32_e32 v132, v129, v191
	v_add_f32_e32 v129, v130, v192
	v_add_f32_e32 v128, v131, v193
	s_waitcnt lgkmcnt(6)
	v_add_f32_e32 v131, v124, v194
	v_add_f32_e32 v130, v125, v195
	v_add_f32_e32 v125, v126, v196
	v_add_f32_e32 v124, v127, v197
	s_waitcnt lgkmcnt(5)
	v_add_f32_e32 v127, v120, v198
	v_add_f32_e32 v126, v121, v199
	v_add_f32_e32 v121, v122, v200
	v_add_f32_e32 v120, v123, v201
	s_waitcnt lgkmcnt(4)
	v_add_f32_e32 v123, v116, v202
	v_add_f32_e32 v122, v117, v203
	v_add_f32_e32 v118, v118, v204
	v_add_f32_e32 v117, v119, v205
	ds_read_b128 v[190:193], v167 offset:16384
	ds_read_b128 v[194:197], v167 offset:17408
	ds_read_b128 v[198:201], v167 offset:18432
	ds_read_b128 v[202:205], v167 offset:19456
	s_waitcnt lgkmcnt(7)
	v_add_f32_e32 v119, v112, v234
	v_add_f32_e32 v116, v113, v235
	v_add_f32_e32 v113, v114, v236
	v_add_f32_e32 v112, v115, v237
	s_waitcnt lgkmcnt(6)
	v_add_f32_e32 v115, v108, v238
	v_add_f32_e32 v114, v109, v239
	v_add_f32_e32 v109, v110, v240
	v_add_f32_e32 v108, v111, v241
	s_waitcnt lgkmcnt(5)
	v_add_f32_e32 v111, v104, v242
	v_add_f32_e32 v110, v105, v243
	v_add_f32_e32 v105, v106, v244
	v_add_f32_e32 v104, v107, v245
	s_waitcnt lgkmcnt(4)
	v_add_f32_e32 v135, v100, v246
	v_add_f32_e32 v107, v101, v247
	v_add_f32_e32 v106, v102, v248
	v_add_f32_e32 v101, v103, v249
	ds_read_b128 v[234:237], v167 offset:20480
	ds_read_b128 v[238:241], v167 offset:21504
	ds_read_b128 v[242:245], v167 offset:22528
	ds_read_b128 v[246:249], v167 offset:23552
	s_waitcnt lgkmcnt(7)
	v_add_f32_e32 v102, v96, v190
	v_add_f32_e32 v100, v97, v191
	v_add_f32_e32 v97, v98, v192
	v_add_f32_e32 v96, v99, v193
	s_waitcnt lgkmcnt(6)
	v_add_f32_e32 v99, v92, v194
	v_add_f32_e32 v98, v93, v195
	v_add_f32_e32 v93, v94, v196
	v_add_f32_e32 v92, v95, v197
	s_waitcnt lgkmcnt(5)
	v_add_f32_e32 v95, v88, v198
	v_add_f32_e32 v94, v89, v199
	v_add_f32_e32 v89, v90, v200
	v_add_f32_e32 v88, v91, v201
	s_waitcnt lgkmcnt(4)
	v_add_f32_e32 v91, v84, v202
	v_add_f32_e32 v90, v85, v203
	v_add_f32_e32 v86, v86, v204
	v_add_f32_e32 v85, v87, v205
	ds_read_b128 v[190:193], v167 offset:24576
	ds_read_b128 v[194:197], v167 offset:25600
	ds_read_b128 v[198:201], v167 offset:26624
	ds_read_b128 v[202:205], v167 offset:27648
	s_waitcnt lgkmcnt(7)
	v_add_f32_e32 v87, v80, v234
	v_add_f32_e32 v84, v81, v235
	v_add_f32_e32 v81, v82, v236
	v_add_f32_e32 v80, v83, v237
	s_waitcnt lgkmcnt(6)
	v_add_f32_e32 v83, v76, v238
	v_add_f32_e32 v82, v77, v239
	v_add_f32_e32 v77, v78, v240
	v_add_f32_e32 v76, v79, v241
	s_waitcnt lgkmcnt(5)
	v_add_f32_e32 v79, v72, v242
	v_add_f32_e32 v78, v73, v243
	v_add_f32_e32 v73, v74, v244
	v_add_f32_e32 v72, v75, v245
	s_waitcnt lgkmcnt(4)
	v_add_f32_e32 v103, v68, v246
	v_add_f32_e32 v75, v69, v247
	v_add_f32_e32 v74, v70, v248
	v_add_f32_e32 v69, v71, v249
	ds_read_b128 v[234:237], v167 offset:28672
	ds_read_b128 v[238:241], v167 offset:29696
	ds_read_b128 v[242:245], v167 offset:30720
	ds_read_b128 v[246:249], v167 offset:31744
	s_waitcnt lgkmcnt(7)
	v_add_f32_e32 v70, v64, v190
	v_add_f32_e32 v68, v65, v191
	v_add_f32_e32 v65, v66, v192
	v_add_f32_e32 v64, v67, v193
	s_waitcnt lgkmcnt(6)
	v_add_f32_e32 v67, v60, v194
	v_add_f32_e32 v66, v61, v195
	v_add_f32_e32 v61, v62, v196
	v_add_f32_e32 v60, v63, v197
	s_waitcnt lgkmcnt(5)
	v_add_f32_e32 v63, v56, v198
	v_add_f32_e32 v62, v57, v199
	v_add_f32_e32 v57, v58, v200
	v_add_f32_e32 v56, v59, v201
	s_waitcnt lgkmcnt(4)
	v_add_f32_e32 v59, v52, v202
	v_add_f32_e32 v58, v53, v203
	v_add_f32_e32 v54, v54, v204
	v_add_f32_e32 v53, v55, v205
	s_waitcnt lgkmcnt(3)
	v_add_f32_e32 v55, v48, v234
	v_add_f32_e32 v52, v49, v235
	v_add_f32_e32 v49, v50, v236
	v_add_f32_e32 v48, v51, v237
	s_waitcnt lgkmcnt(2)
	v_add_f32_e32 v51, v44, v238
	v_add_f32_e32 v50, v45, v239
	v_add_f32_e32 v45, v46, v240
	v_add_f32_e32 v44, v47, v241
	s_waitcnt lgkmcnt(1)
	v_add_f32_e32 v47, v40, v242
	v_add_f32_e32 v46, v41, v243
	v_add_f32_e32 v41, v42, v244
	v_add_f32_e32 v40, v43, v245
	s_waitcnt lgkmcnt(0)
	v_add_f32_e32 v43, v36, v246
	v_add_f32_e32 v42, v37, v247
	v_add_f32_e32 v37, v38, v248
	v_add_f32_e32 v36, v39, v249
	v_mul_f32_e32 v38, v151, v151
	v_fmac_f32_e32 v38, v165, v165
	v_fmac_f32_e32 v38, v133, v133
	v_fmac_f32_e32 v38, v119, v119
	v_fmac_f32_e32 v38, v102, v102
	v_fmac_f32_e32 v38, v87, v87
	v_fmac_f32_e32 v38, v70, v70
	v_fmac_f32_e32 v38, v55, v55
	v_mul_f32_e32 v71, v148, v148
	ds_swizzle_b32 v39, v38 offset:swizzle(SWAP,1)
	v_fmac_f32_e32 v71, v161, v161
	v_fmac_f32_e32 v71, v132, v132
	v_fmac_f32_e32 v71, v116, v116
	v_fmac_f32_e32 v71, v100, v100
	v_fmac_f32_e32 v71, v84, v84
	v_fmac_f32_e32 v71, v68, v68
	s_waitcnt lgkmcnt(0)
	v_add_f32_e32 v38, v38, v39
	v_fmac_f32_e32 v71, v52, v52
	ds_swizzle_b32 v39, v38 offset:swizzle(SWAP,2)
	ds_swizzle_b32 v167, v71 offset:swizzle(SWAP,1)
	v_mul_f32_e32 v168, v145, v145
	v_mul_f32_e32 v169, v144, v144
	v_fmac_f32_e32 v168, v160, v160
	s_waitcnt lgkmcnt(1)
	v_add_f32_e32 v38, v38, v39
	s_waitcnt lgkmcnt(0)
	v_add_f32_e32 v71, v71, v167
	ds_swizzle_b32 v39, v38 offset:swizzle(SWAP,4)
	ds_swizzle_b32 v167, v71 offset:swizzle(SWAP,2)
	v_fmac_f32_e32 v169, v0, v0
	v_fmac_f32_e32 v168, v129, v129
	v_fmac_f32_e32 v169, v128, v128
	s_waitcnt lgkmcnt(1)
	v_add_f32_e32 v38, v38, v39
	s_waitcnt lgkmcnt(0)
	v_add_f32_e32 v71, v71, v167
	ds_swizzle_b32 v39, v38 offset:swizzle(SWAP,8)
	ds_swizzle_b32 v167, v71 offset:swizzle(SWAP,4)
	v_fmac_f32_e32 v168, v113, v113
	v_fmac_f32_e32 v169, v112, v112
	v_fmac_f32_e32 v168, v97, v97
	s_waitcnt lgkmcnt(1)
	v_add_f32_e32 v38, v38, v39
	s_waitcnt lgkmcnt(0)
	v_add_f32_e32 v71, v71, v167
	ds_swizzle_b32 v39, v38 offset:swizzle(SWAP,16)
	ds_swizzle_b32 v167, v71 offset:swizzle(SWAP,8)
	v_fmac_f32_e32 v169, v96, v96
	v_fmac_f32_e32 v168, v81, v81
	v_fmac_f32_e32 v169, v80, v80
	v_fmac_f32_e32 v168, v65, v65
	v_fmac_f32_e32 v169, v64, v64
	v_fmac_f32_e32 v168, v49, v49
	v_fmac_f32_e32 v169, v48, v48
	s_waitcnt lgkmcnt(1)
	v_add_f32_e32 v38, v38, v39
	ds_swizzle_b32 v39, v168 offset:swizzle(SWAP,1)
	ds_swizzle_b32 v170, v169 offset:swizzle(SWAP,1)
	s_waitcnt lgkmcnt(2)
	v_add_f32_e32 v71, v71, v167
	ds_swizzle_b32 v167, v71 offset:swizzle(SWAP,16)
	v_mul_f32_e32 v173, v140, v140
	s_waitcnt lgkmcnt(2)
	v_add_f32_e32 v39, v168, v39
	s_waitcnt lgkmcnt(1)
	v_add_f32_e32 v168, v169, v170
	v_mul_f32_e32 v170, v147, v147
	v_fmac_f32_e32 v170, v163, v163
	s_waitcnt lgkmcnt(0)
	v_add_f32_e32 v71, v71, v167
	ds_swizzle_b32 v167, v39 offset:swizzle(SWAP,2)
	ds_swizzle_b32 v169, v168 offset:swizzle(SWAP,2)
	v_fmac_f32_e32 v170, v131, v131
	v_fmac_f32_e32 v170, v115, v115
	v_fmac_f32_e32 v170, v99, v99
	v_fmac_f32_e32 v170, v83, v83
	v_fmac_f32_e32 v170, v67, v67
	s_waitcnt lgkmcnt(1)
	v_add_f32_e32 v39, v39, v167
	s_waitcnt lgkmcnt(0)
	v_add_f32_e32 v168, v168, v169
	v_fmac_f32_e32 v170, v51, v51
	ds_swizzle_b32 v167, v39 offset:swizzle(SWAP,4)
	ds_swizzle_b32 v169, v168 offset:swizzle(SWAP,4)
	ds_swizzle_b32 v171, v170 offset:swizzle(SWAP,1)
	v_fmamk_f32 v71, v71, 0x3b800000, v214
	v_rsq_f32_e32 v71, v71
	s_waitcnt lgkmcnt(2)
	v_add_f32_e32 v39, v39, v167
	s_waitcnt lgkmcnt(1)
	v_add_f32_e32 v168, v168, v169
	s_waitcnt lgkmcnt(0)
	v_add_f32_e32 v170, v170, v171
	ds_swizzle_b32 v167, v39 offset:swizzle(SWAP,8)
	ds_swizzle_b32 v169, v168 offset:swizzle(SWAP,8)
	ds_swizzle_b32 v171, v170 offset:swizzle(SWAP,2)
	v_fmac_f32_e32 v173, v156, v156
	v_fmac_f32_e32 v173, v124, v124
	s_waitcnt lgkmcnt(2)
	v_add_f32_e32 v39, v39, v167
	s_waitcnt lgkmcnt(1)
	v_add_f32_e32 v168, v168, v169
	s_waitcnt lgkmcnt(0)
	v_add_f32_e32 v170, v170, v171
	ds_swizzle_b32 v167, v39 offset:swizzle(SWAP,16)
	ds_swizzle_b32 v169, v168 offset:swizzle(SWAP,16)
	ds_swizzle_b32 v171, v170 offset:swizzle(SWAP,4)
	v_fmac_f32_e32 v173, v108, v108
	v_fmac_f32_e32 v173, v92, v92
	s_waitcnt lgkmcnt(2)
	v_add_f32_e32 v39, v39, v167
	s_waitcnt lgkmcnt(1)
	v_add_f32_e32 v167, v168, v169
	s_waitcnt lgkmcnt(0)
	v_add_f32_e32 v168, v170, v171
	v_mul_f32_e32 v170, v146, v146
	v_fmac_f32_e32 v170, v162, v162
	v_fmac_f32_e32 v170, v130, v130
	v_fmac_f32_e32 v170, v114, v114
	v_fmac_f32_e32 v170, v98, v98
	v_fmac_f32_e32 v170, v82, v82
	v_fmac_f32_e32 v170, v66, v66
	v_fmac_f32_e32 v170, v50, v50
	ds_swizzle_b32 v169, v168 offset:swizzle(SWAP,8)
	ds_swizzle_b32 v171, v170 offset:swizzle(SWAP,1)
	v_fmamk_f32 v39, v39, 0x3b800000, v214
	v_fmamk_f32 v167, v167, 0x3b800000, v214
	v_rsq_f32_e32 v39, v39
	s_waitcnt lgkmcnt(1)
	v_add_f32_e32 v168, v168, v169
	s_waitcnt lgkmcnt(0)
	v_add_f32_e32 v170, v170, v171
	ds_swizzle_b32 v169, v168 offset:swizzle(SWAP,16)
	ds_swizzle_b32 v171, v170 offset:swizzle(SWAP,2)
	v_rsq_f32_e32 v172, v167
	v_mul_f32_e32 v167, 0x3f4ccccd, v71
	v_mul_f32_e32 v71, 0x3f4ccccd, v39
	s_waitcnt lgkmcnt(1)
	v_add_f32_e32 v168, v168, v169
	s_waitcnt lgkmcnt(0)
	v_add_f32_e32 v169, v170, v171
	v_mul_f32_e32 v171, v141, v141
	v_fmac_f32_e32 v171, v157, v157
	v_fmac_f32_e32 v171, v125, v125
	v_fmac_f32_e32 v171, v109, v109
	v_fmac_f32_e32 v171, v93, v93
	v_fmac_f32_e32 v171, v77, v77
	v_fmac_f32_e32 v171, v61, v61
	v_fmac_f32_e32 v171, v45, v45
	v_mul_f32_e32 v39, 0x3f4ccccd, v172
	ds_swizzle_b32 v170, v169 offset:swizzle(SWAP,4)
	ds_swizzle_b32 v172, v171 offset:swizzle(SWAP,1)
	v_fmac_f32_e32 v173, v76, v76
	v_fmac_f32_e32 v173, v60, v60
	v_fmac_f32_e32 v173, v44, v44
	s_waitcnt lgkmcnt(1)
	v_add_f32_e32 v169, v169, v170
	s_waitcnt lgkmcnt(0)
	v_add_f32_e32 v171, v171, v172
	ds_swizzle_b32 v170, v169 offset:swizzle(SWAP,8)
	ds_swizzle_b32 v172, v171 offset:swizzle(SWAP,2)
	ds_swizzle_b32 v174, v173 offset:swizzle(SWAP,1)
	v_mul_f32_e32 v177, v136, v136
	v_fmac_f32_e32 v177, v152, v152
	s_waitcnt lgkmcnt(2)
	v_add_f32_e32 v169, v169, v170
	s_waitcnt lgkmcnt(1)
	v_add_f32_e32 v171, v171, v172
	s_waitcnt lgkmcnt(0)
	v_add_f32_e32 v173, v173, v174
	ds_swizzle_b32 v170, v169 offset:swizzle(SWAP,16)
	ds_swizzle_b32 v172, v171 offset:swizzle(SWAP,4)
	ds_swizzle_b32 v174, v173 offset:swizzle(SWAP,2)
	v_fmac_f32_e32 v177, v120, v120
	v_fmac_f32_e32 v177, v104, v104
	s_waitcnt lgkmcnt(2)
	v_add_f32_e32 v169, v169, v170
	s_waitcnt lgkmcnt(1)
	v_add_f32_e32 v170, v171, v172
	s_waitcnt lgkmcnt(0)
	v_add_f32_e32 v172, v173, v174
	v_mul_f32_e32 v174, v143, v143
	v_fmac_f32_e32 v174, v159, v159
	ds_swizzle_b32 v171, v170 offset:swizzle(SWAP,8)
	ds_swizzle_b32 v173, v172 offset:swizzle(SWAP,4)
	v_fmac_f32_e32 v174, v127, v127
	v_fmac_f32_e32 v174, v111, v111
	v_fmac_f32_e32 v174, v95, v95
	v_fmac_f32_e32 v174, v79, v79
	v_fmac_f32_e32 v174, v63, v63
	s_waitcnt lgkmcnt(1)
	v_add_f32_e32 v170, v170, v171
	s_waitcnt lgkmcnt(0)
	v_add_f32_e32 v172, v172, v173
	v_fmac_f32_e32 v174, v47, v47
	ds_swizzle_b32 v171, v170 offset:swizzle(SWAP,16)
	ds_swizzle_b32 v173, v172 offset:swizzle(SWAP,8)
	ds_swizzle_b32 v175, v174 offset:swizzle(SWAP,1)
	v_fmac_f32_e32 v177, v88, v88
	v_fmac_f32_e32 v177, v72, v72
	s_waitcnt lgkmcnt(2)
	v_add_f32_e32 v170, v170, v171
	s_waitcnt lgkmcnt(1)
	v_add_f32_e32 v171, v172, v173
	s_waitcnt lgkmcnt(0)
	v_add_f32_e32 v172, v174, v175
	v_mul_f32_e32 v174, v142, v142
	v_fmac_f32_e32 v174, v158, v158
	v_fmac_f32_e32 v174, v126, v126
	v_fmac_f32_e32 v174, v110, v110
	v_fmac_f32_e32 v174, v94, v94
	v_fmac_f32_e32 v174, v78, v78
	v_fmac_f32_e32 v174, v62, v62
	v_fmac_f32_e32 v174, v46, v46
	ds_swizzle_b32 v173, v172 offset:swizzle(SWAP,2)
	ds_swizzle_b32 v175, v174 offset:swizzle(SWAP,1)
	ds_swizzle_b32 v176, v171 offset:swizzle(SWAP,16)
	v_fmac_f32_e32 v177, v56, v56
	v_fmac_f32_e32 v177, v40, v40
	s_waitcnt lgkmcnt(2)
	v_add_f32_e32 v172, v172, v173
	s_waitcnt lgkmcnt(1)
	v_add_f32_e32 v174, v174, v175
	ds_swizzle_b32 v173, v172 offset:swizzle(SWAP,4)
	ds_swizzle_b32 v175, v174 offset:swizzle(SWAP,2)
	s_waitcnt lgkmcnt(2)
	v_add_f32_e32 v171, v171, v176
	ds_swizzle_b32 v178, v177 offset:swizzle(SWAP,1)
	s_waitcnt vmcnt(14)
	v_mul_f32_e32 v183, v134, v134
	s_waitcnt lgkmcnt(2)
	v_add_f32_e32 v172, v172, v173
	s_waitcnt lgkmcnt(1)
	v_add_f32_e32 v174, v174, v175
	ds_swizzle_b32 v173, v172 offset:swizzle(SWAP,8)
	ds_swizzle_b32 v175, v174 offset:swizzle(SWAP,4)
	v_fmac_f32_e32 v183, v149, v149
	v_fmac_f32_e32 v183, v117, v117
	v_fmac_f32_e32 v183, v101, v101
	s_waitcnt lgkmcnt(1)
	v_add_f32_e32 v172, v172, v173
	s_waitcnt lgkmcnt(0)
	v_add_f32_e32 v174, v174, v175
	ds_swizzle_b32 v173, v172 offset:swizzle(SWAP,16)
	ds_swizzle_b32 v175, v174 offset:swizzle(SWAP,8)
	v_fmac_f32_e32 v183, v85, v85
	v_fmac_f32_e32 v183, v69, v69
	v_fmac_f32_e32 v183, v53, v53
	s_waitcnt lgkmcnt(1)
	v_add_f32_e32 v172, v172, v173
	s_waitcnt lgkmcnt(0)
	v_add_f32_e32 v173, v174, v175
	v_mul_f32_e32 v175, v137, v137
	v_fmac_f32_e32 v175, v153, v153
	v_fmac_f32_e32 v175, v121, v121
	v_fmac_f32_e32 v175, v105, v105
	v_fmac_f32_e32 v175, v89, v89
	v_fmac_f32_e32 v175, v73, v73
	v_fmac_f32_e32 v175, v57, v57
	v_fmac_f32_e32 v175, v41, v41
	ds_swizzle_b32 v174, v173 offset:swizzle(SWAP,16)
	ds_swizzle_b32 v176, v175 offset:swizzle(SWAP,1)
	v_fmac_f32_e32 v183, v36, v36
	ds_swizzle_b32 v185, v183 offset:swizzle(SWAP,1)
	v_fmamk_f32 v38, v38, 0x3b800000, v214
	s_waitcnt lgkmcnt(2)
	v_add_f32_e32 v173, v173, v174
	s_waitcnt lgkmcnt(1)
	v_add_f32_e32 v174, v175, v176
	v_add_f32_e32 v176, v177, v178
	v_mul_f32_e32 v178, v166, v166
	v_fmac_f32_e32 v178, v155, v155
	ds_swizzle_b32 v175, v174 offset:swizzle(SWAP,2)
	ds_swizzle_b32 v177, v176 offset:swizzle(SWAP,2)
	v_fmac_f32_e32 v178, v123, v123
	v_fmac_f32_e32 v178, v135, v135
	v_fmac_f32_e32 v178, v91, v91
	v_fmac_f32_e32 v178, v103, v103
	v_fmac_f32_e32 v178, v59, v59
	s_waitcnt lgkmcnt(1)
	v_add_f32_e32 v174, v174, v175
	s_waitcnt lgkmcnt(0)
	v_add_f32_e32 v176, v176, v177
	v_fmac_f32_e32 v178, v43, v43
	ds_swizzle_b32 v175, v174 offset:swizzle(SWAP,4)
	ds_swizzle_b32 v177, v176 offset:swizzle(SWAP,4)
	ds_swizzle_b32 v179, v178 offset:swizzle(SWAP,1)
	v_add_f32_e32 v183, v183, v185
	ds_swizzle_b32 v185, v183 offset:swizzle(SWAP,2)
	s_waitcnt lgkmcnt(3)
	v_add_f32_e32 v174, v174, v175
	s_waitcnt lgkmcnt(2)
	v_add_f32_e32 v176, v176, v177
	s_waitcnt lgkmcnt(1)
	v_add_f32_e32 v178, v178, v179
	ds_swizzle_b32 v175, v174 offset:swizzle(SWAP,8)
	ds_swizzle_b32 v177, v176 offset:swizzle(SWAP,8)
	ds_swizzle_b32 v179, v178 offset:swizzle(SWAP,2)
	v_rsq_f32_e32 v38, v38
	v_fmamk_f32 v168, v168, 0x3b800000, v214
	s_waitcnt lgkmcnt(2)
	v_add_f32_e32 v174, v174, v175
	s_waitcnt lgkmcnt(1)
	v_add_f32_e32 v176, v176, v177
	s_waitcnt lgkmcnt(0)
	v_add_f32_e32 v178, v178, v179
	ds_swizzle_b32 v175, v174 offset:swizzle(SWAP,16)
	ds_swizzle_b32 v177, v176 offset:swizzle(SWAP,16)
	ds_swizzle_b32 v179, v178 offset:swizzle(SWAP,4)
	v_mul_f32_e32 v38, 0x3f4ccccd, v38
	v_rsq_f32_e32 v168, v168
	s_waitcnt lgkmcnt(2)
	v_add_f32_e32 v174, v174, v175
	s_waitcnt lgkmcnt(1)
	v_add_f32_e32 v175, v176, v177
	s_waitcnt lgkmcnt(0)
	v_add_f32_e32 v176, v178, v179
	v_mul_f32_e32 v178, v139, v139
	v_fmac_f32_e32 v178, v154, v154
	v_fmac_f32_e32 v178, v122, v122
	v_fmac_f32_e32 v178, v107, v107
	v_fmac_f32_e32 v178, v90, v90
	v_fmac_f32_e32 v178, v75, v75
	v_fmac_f32_e32 v178, v58, v58
	v_fmac_f32_e32 v178, v42, v42
	ds_swizzle_b32 v177, v176 offset:swizzle(SWAP,8)
	ds_swizzle_b32 v181, v178 offset:swizzle(SWAP,1)
	v_lshlrev_b32_e32 v179, 2, v217
	global_load_dword v180, v179, s[52:53]
	global_load_dword v184, v179, s[52:53] offset:128
	s_waitcnt lgkmcnt(1)
	v_add_f32_e32 v176, v176, v177
	s_waitcnt lgkmcnt(0)
	v_add_f32_e32 v178, v178, v181
	ds_swizzle_b32 v177, v176 offset:swizzle(SWAP,16)
	ds_swizzle_b32 v181, v178 offset:swizzle(SWAP,2)
	s_waitcnt vmcnt(15)
	v_lshlrev_b32_e32 v189, 12, v218
	v_mul_f32_e32 v165, v165, v38
	v_mul_f32_e32 v151, v151, v38
	s_waitcnt lgkmcnt(1)
	v_add_f32_e32 v176, v176, v177
	s_waitcnt lgkmcnt(0)
	v_add_f32_e32 v177, v178, v181
	v_mul_f32_e32 v181, v138, v138
	v_fmac_f32_e32 v181, v150, v150
	v_fmac_f32_e32 v181, v118, v118
	v_fmac_f32_e32 v181, v106, v106
	v_fmac_f32_e32 v181, v86, v86
	v_fmac_f32_e32 v181, v74, v74
	v_fmac_f32_e32 v181, v54, v54
	v_fmac_f32_e32 v181, v37, v37
	ds_swizzle_b32 v178, v177 offset:swizzle(SWAP,4)
	ds_swizzle_b32 v182, v181 offset:swizzle(SWAP,1)
	v_fmamk_f32 v169, v169, 0x3b800000, v214
	v_mul_f32_e32 v161, v161, v167
	v_mul_f32_e32 v148, v148, v167
	s_waitcnt lgkmcnt(1)
	v_add_f32_e32 v177, v177, v178
	s_waitcnt lgkmcnt(0)
	v_add_f32_e32 v178, v181, v182
	ds_swizzle_b32 v181, v178 offset:swizzle(SWAP,2)
	ds_swizzle_b32 v182, v177 offset:swizzle(SWAP,8)
	v_rsq_f32_e32 v169, v169
	v_mul_f32_e32 v160, v160, v71
	v_mul_f32_e32 v145, v145, v71
	s_waitcnt lgkmcnt(1)
	v_add_f32_e32 v178, v178, v181
	s_waitcnt lgkmcnt(0)
	v_add_f32_e32 v177, v177, v182
	v_add_f32_e32 v182, v183, v185
	ds_swizzle_b32 v181, v178 offset:swizzle(SWAP,4)
	ds_swizzle_b32 v183, v182 offset:swizzle(SWAP,4)
	ds_swizzle_b32 v185, v177 offset:swizzle(SWAP,16)
	v_fmamk_f32 v170, v170, 0x3b800000, v214
	v_mul_f32_e32 v0, v0, v39
	s_waitcnt lgkmcnt(2)
	v_add_f32_e32 v178, v178, v181
	s_waitcnt lgkmcnt(1)
	v_add_f32_e32 v182, v182, v183
	ds_swizzle_b32 v181, v178 offset:swizzle(SWAP,8)
	ds_swizzle_b32 v183, v182 offset:swizzle(SWAP,8)
	s_waitcnt lgkmcnt(2)
	v_add_f32_e32 v177, v177, v185
	v_mul_f32_e32 v144, v144, v39
	v_mul_f32_e32 v168, 0x3f4ccccd, v168
	s_waitcnt lgkmcnt(1)
	v_add_f32_e32 v178, v178, v181
	s_waitcnt lgkmcnt(0)
	v_add_f32_e32 v182, v182, v183
	ds_swizzle_b32 v181, v178 offset:swizzle(SWAP,16)
	ds_swizzle_b32 v183, v182 offset:swizzle(SWAP,16)
	v_rsq_f32_e32 v170, v170
	v_fmamk_f32 v171, v171, 0x3b800000, v214
	v_mul_f32_e32 v163, v163, v168
	s_waitcnt lgkmcnt(1)
	v_add_f32_e32 v178, v178, v181
	s_waitcnt lgkmcnt(0)
	v_add_f32_e32 v181, v182, v183
	global_load_dword v182, v179, s[52:53] offset:256
	global_load_dword v183, v179, s[52:53] offset:384
	global_load_dword v185, v179, s[52:53] offset:512
	global_load_dword v186, v179, s[52:53] offset:640
	global_load_dword v187, v179, s[52:53] offset:768
	global_load_dword v188, v179, s[52:53] offset:896
	v_add3_u32 v179, s95, v189, v179
	s_waitcnt lgkmcnt(0)
	v_mul_f32_e32 v169, 0x3f4ccccd, v169
	v_rsq_f32_e32 v171, v171
	v_fmamk_f32 v172, v172, 0x3b800000, v214
	v_mul_f32_e32 v162, v162, v169
	v_mul_f32_e32 v170, 0x3f4ccccd, v170
	v_rsq_f32_e32 v172, v172
	v_fmamk_f32 v173, v173, 0x3b800000, v214
	v_mul_f32_e32 v157, v157, v170
	v_mul_f32_e32 v171, 0x3f4ccccd, v171
	v_rsq_f32_e32 v173, v173
	v_fmamk_f32 v174, v174, 0x3b800000, v214
	v_mul_f32_e32 v156, v156, v171
	v_mul_f32_e32 v172, 0x3f4ccccd, v172
	v_rsq_f32_e32 v174, v174
	v_fmamk_f32 v175, v175, 0x3b800000, v214
	v_mul_f32_e32 v159, v159, v172
	v_rsq_f32_e32 v175, v175
	v_mul_f32_e32 v173, 0x3f4ccccd, v173
	v_fmamk_f32 v176, v176, 0x3b800000, v214
	v_mul_f32_e32 v158, v158, v173
	v_mul_f32_e32 v174, 0x3f4ccccd, v174
	v_rsq_f32_e32 v176, v176
	s_waitcnt vmcnt(7)
	v_mul_f32_e32 v165, v165, v180
	s_waitcnt vmcnt(6)
	v_mul_f32_e32 v151, v151, v184
	v_mul_f32_e32 v161, v161, v180
	ds_write2_b32 v179, v165, v151 offset1:32
	v_mul_f32_e32 v148, v148, v184
	v_add_u32_e32 v151, 0x400, v179
	v_mul_f32_e32 v160, v160, v180
	ds_write2_b32 v151, v161, v148 offset1:32
	v_mul_f32_e32 v145, v145, v184
	v_add_u32_e32 v148, 0x800, v179
	v_mul_f32_e32 v0, v0, v180
	ds_write2_b32 v148, v160, v145 offset1:32
	v_mul_f32_e32 v144, v144, v184
	v_add_u32_e32 v145, 0xc00, v179
	ds_write2_b32 v145, v0, v144 offset1:32
	v_mul_f32_e32 v0, v147, v168
	v_mul_f32_e32 v163, v163, v180
	v_mul_f32_e32 v0, v0, v184
	v_add_u32_e32 v144, 0x2000, v179
	ds_write2_b32 v144, v163, v0 offset1:32
	v_mul_f32_e32 v0, v146, v169
	v_mul_f32_e32 v162, v162, v180
	v_mul_f32_e32 v0, v0, v184
	v_add_u32_e32 v146, 0x2400, v179
	ds_write2_b32 v146, v162, v0 offset1:32
	v_mul_f32_e32 v0, v141, v170
	v_mul_f32_e32 v157, v157, v180
	v_mul_f32_e32 v0, v0, v184
	v_add_u32_e32 v141, 0x2800, v179
	ds_write2_b32 v141, v157, v0 offset1:32
	v_mul_f32_e32 v0, v140, v171
	v_mul_f32_e32 v156, v156, v180
	v_mul_f32_e32 v0, v0, v184
	v_add_u32_e32 v140, 0x2c00, v179
	ds_write2_b32 v140, v156, v0 offset1:32
	v_mul_f32_e32 v0, v143, v172
	v_mul_f32_e32 v159, v159, v180
	v_mul_f32_e32 v0, v0, v184
	v_add_u32_e32 v143, 0x4000, v179
	ds_write2_b32 v143, v159, v0 offset1:32
	v_mul_f32_e32 v0, v142, v173
	v_mul_f32_e32 v158, v158, v180
	v_mul_f32_e32 v0, v0, v184
	v_add_u32_e32 v142, 0x4400, v179
	v_fmamk_f32 v177, v177, 0x3b800000, v214
	v_mul_f32_e32 v153, v153, v174
	ds_write2_b32 v142, v158, v0 offset1:32
	v_mul_f32_e32 v0, v137, v174
	v_mul_f32_e32 v175, 0x3f4ccccd, v175
	v_rsq_f32_e32 v177, v177
	v_mul_f32_e32 v153, v153, v180
	v_mul_f32_e32 v0, v0, v184
	v_add_u32_e32 v137, 0x4800, v179
	v_fmamk_f32 v178, v178, 0x3b800000, v214
	v_mul_f32_e32 v152, v152, v175
	ds_write2_b32 v137, v153, v0 offset1:32
	v_mul_f32_e32 v0, v136, v175
	v_rsq_f32_e32 v178, v178
	v_mul_f32_e32 v176, 0x3f4ccccd, v176
	v_mul_f32_e32 v152, v152, v180
	v_mul_f32_e32 v0, v0, v184
	v_add_u32_e32 v136, 0x4c00, v179
	v_fmamk_f32 v181, v181, 0x3b800000, v214
	v_mul_f32_e32 v155, v155, v176
	ds_write2_b32 v136, v152, v0 offset1:32
	v_mul_f32_e32 v0, v166, v176
	v_rsq_f32_e32 v181, v181
	v_mul_f32_e32 v177, 0x3f4ccccd, v177
	v_mul_f32_e32 v155, v155, v180
	v_mul_f32_e32 v0, v0, v184
	v_add_u32_e32 v147, 0x6000, v179
	v_mul_f32_e32 v154, v154, v177
	ds_write2_b32 v147, v155, v0 offset1:32
	v_mul_f32_e32 v0, v139, v177
	v_mul_f32_e32 v178, 0x3f4ccccd, v178
	v_mul_f32_e32 v154, v154, v180
	v_mul_f32_e32 v0, v0, v184
	v_add_u32_e32 v139, 0x6400, v179
	v_mul_f32_e32 v150, v150, v178
	ds_write2_b32 v139, v154, v0 offset1:32
	v_mul_f32_e32 v0, v138, v178
	v_mul_f32_e32 v181, 0x3f4ccccd, v181
	v_mul_f32_e32 v150, v180, v150
	v_mul_f32_e32 v0, v0, v184
	v_add_u32_e32 v138, 0x6800, v179
	v_mul_f32_e32 v149, v149, v181
	ds_write2_b32 v138, v150, v0 offset1:32
	v_mul_f32_e32 v0, v134, v181
	v_mul_f32_e32 v149, v180, v149
	v_mul_f32_e32 v0, v184, v0
	v_add_u32_e32 v134, 0x6c00, v179
	ds_write2_b32 v134, v149, v0 offset1:32
	v_mul_f32_e32 v0, v133, v38
	v_mul_f32_e32 v119, v119, v38
	s_waitcnt vmcnt(5)
	v_mul_f32_e32 v0, v0, v182
	s_waitcnt vmcnt(4)
	v_mul_f32_e32 v119, v119, v183
	v_mul_f32_e32 v132, v132, v167
	ds_write2_b32 v179, v0, v119 offset0:64 offset1:96
	v_mul_f32_e32 v0, v116, v167
	v_mul_f32_e32 v132, v132, v182
	v_mul_f32_e32 v0, v0, v183
	v_mul_f32_e32 v129, v129, v71
	ds_write2_b32 v151, v132, v0 offset0:64 offset1:96
	v_mul_f32_e32 v0, v113, v71
	v_mul_f32_e32 v129, v129, v182
	v_mul_f32_e32 v0, v0, v183
	v_mul_f32_e32 v128, v128, v39
	ds_write2_b32 v148, v129, v0 offset0:64 offset1:96
	v_mul_f32_e32 v0, v112, v39
	v_mul_f32_e32 v128, v128, v182
	v_mul_f32_e32 v0, v0, v183
	v_mul_f32_e32 v131, v131, v168
	ds_write2_b32 v145, v128, v0 offset0:64 offset1:96
	v_mul_f32_e32 v0, v115, v168
	v_mul_f32_e32 v131, v131, v182
	v_mul_f32_e32 v0, v0, v183
	v_mul_f32_e32 v130, v130, v169
	ds_write2_b32 v144, v131, v0 offset0:64 offset1:96
	v_mul_f32_e32 v0, v114, v169
	v_mul_f32_e32 v130, v130, v182
	v_mul_f32_e32 v0, v0, v183
	v_mul_f32_e32 v125, v125, v170
	ds_write2_b32 v146, v130, v0 offset0:64 offset1:96
	v_mul_f32_e32 v0, v109, v170
	v_mul_f32_e32 v125, v125, v182
	v_mul_f32_e32 v0, v0, v183
	v_mul_f32_e32 v124, v124, v171
	ds_write2_b32 v141, v125, v0 offset0:64 offset1:96
	v_mul_f32_e32 v0, v108, v171
	v_mul_f32_e32 v124, v124, v182
	v_mul_f32_e32 v0, v0, v183
	v_mul_f32_e32 v127, v127, v172
	ds_write2_b32 v140, v124, v0 offset0:64 offset1:96
	v_mul_f32_e32 v0, v111, v172
	v_mul_f32_e32 v127, v127, v182
	v_mul_f32_e32 v0, v0, v183
	v_mul_f32_e32 v126, v126, v173
	ds_write2_b32 v143, v127, v0 offset0:64 offset1:96
	v_mul_f32_e32 v0, v110, v173
	v_mul_f32_e32 v126, v126, v182
	v_mul_f32_e32 v0, v0, v183
	v_mul_f32_e32 v121, v121, v174
	ds_write2_b32 v142, v126, v0 offset0:64 offset1:96
	v_mul_f32_e32 v0, v105, v174
	v_mul_f32_e32 v121, v121, v182
	v_mul_f32_e32 v0, v0, v183
	v_mul_f32_e32 v120, v120, v175
	ds_write2_b32 v137, v121, v0 offset0:64 offset1:96
	v_mul_f32_e32 v0, v104, v175
	v_mul_f32_e32 v120, v120, v182
	v_mul_f32_e32 v0, v0, v183
	v_mul_f32_e32 v123, v123, v176
	ds_write2_b32 v136, v120, v0 offset0:64 offset1:96
	v_mul_f32_e32 v0, v135, v176
	v_mul_f32_e32 v123, v123, v182
	v_mul_f32_e32 v0, v0, v183
	v_mul_f32_e32 v122, v122, v177
	ds_write2_b32 v147, v123, v0 offset0:64 offset1:96
	v_mul_f32_e32 v0, v107, v177
	v_mul_f32_e32 v122, v122, v182
	v_mul_f32_e32 v0, v0, v183
	v_mul_f32_e32 v118, v118, v178
	ds_write2_b32 v139, v122, v0 offset0:64 offset1:96
	v_mul_f32_e32 v0, v106, v178
	v_mul_f32_e32 v118, v118, v182
	v_mul_f32_e32 v0, v0, v183
	v_mul_f32_e32 v117, v117, v181
	ds_write2_b32 v138, v118, v0 offset0:64 offset1:96
	v_mul_f32_e32 v0, v101, v181
	v_mul_f32_e32 v117, v182, v117
	v_mul_f32_e32 v0, v183, v0
	ds_write2_b32 v134, v117, v0 offset0:64 offset1:96
	v_mul_f32_e32 v0, v102, v38
	v_mul_f32_e32 v87, v87, v38
	s_waitcnt vmcnt(3)
	v_mul_f32_e32 v0, v0, v185
	s_waitcnt vmcnt(2)
	v_mul_f32_e32 v87, v87, v186
	v_mul_f32_e32 v100, v100, v167
	ds_write2_b32 v179, v0, v87 offset0:128 offset1:160
	v_mul_f32_e32 v0, v84, v167
	v_mul_f32_e32 v100, v100, v185
	v_mul_f32_e32 v0, v0, v186
	v_mul_f32_e32 v97, v97, v71
	ds_write2_b32 v151, v100, v0 offset0:128 offset1:160
	v_mul_f32_e32 v0, v81, v71
	v_mul_f32_e32 v97, v97, v185
	v_mul_f32_e32 v0, v0, v186
	v_mul_f32_e32 v96, v96, v39
	ds_write2_b32 v148, v97, v0 offset0:128 offset1:160
	v_mul_f32_e32 v0, v80, v39
	v_mul_f32_e32 v96, v96, v185
	v_mul_f32_e32 v0, v0, v186
	v_mul_f32_e32 v99, v99, v168
	ds_write2_b32 v145, v96, v0 offset0:128 offset1:160
	v_mul_f32_e32 v0, v83, v168
	v_mul_f32_e32 v99, v99, v185
	v_mul_f32_e32 v0, v0, v186
	v_mul_f32_e32 v98, v98, v169
	ds_write2_b32 v144, v99, v0 offset0:128 offset1:160
	v_mul_f32_e32 v0, v82, v169
	v_mul_f32_e32 v98, v98, v185
	v_mul_f32_e32 v0, v0, v186
	v_mul_f32_e32 v93, v93, v170
	ds_write2_b32 v146, v98, v0 offset0:128 offset1:160
	v_mul_f32_e32 v0, v77, v170
	v_mul_f32_e32 v93, v93, v185
	v_mul_f32_e32 v0, v0, v186
	v_mul_f32_e32 v92, v92, v171
	ds_write2_b32 v141, v93, v0 offset0:128 offset1:160
	v_mul_f32_e32 v0, v76, v171
	v_mul_f32_e32 v92, v92, v185
	v_mul_f32_e32 v0, v0, v186
	v_mul_f32_e32 v95, v95, v172
	ds_write2_b32 v140, v92, v0 offset0:128 offset1:160
	v_mul_f32_e32 v0, v79, v172
	v_mul_f32_e32 v95, v95, v185
	v_mul_f32_e32 v0, v0, v186
	v_mul_f32_e32 v94, v94, v173
	ds_write2_b32 v143, v95, v0 offset0:128 offset1:160
	v_mul_f32_e32 v0, v78, v173
	v_mul_f32_e32 v94, v94, v185
	v_mul_f32_e32 v0, v0, v186
	v_mul_f32_e32 v89, v89, v174
	ds_write2_b32 v142, v94, v0 offset0:128 offset1:160
	v_mul_f32_e32 v0, v73, v174
	v_mul_f32_e32 v89, v89, v185
	v_mul_f32_e32 v0, v0, v186
	v_mul_f32_e32 v88, v88, v175
	ds_write2_b32 v137, v89, v0 offset0:128 offset1:160
	v_mul_f32_e32 v0, v72, v175
	v_mul_f32_e32 v88, v88, v185
	v_mul_f32_e32 v0, v0, v186
	v_mul_f32_e32 v91, v91, v176
	ds_write2_b32 v136, v88, v0 offset0:128 offset1:160
	v_mul_f32_e32 v0, v103, v176
	v_mul_f32_e32 v91, v91, v185
	v_mul_f32_e32 v0, v0, v186
	v_mul_f32_e32 v90, v90, v177
	ds_write2_b32 v147, v91, v0 offset0:128 offset1:160
	v_mul_f32_e32 v0, v75, v177
	v_mul_f32_e32 v90, v90, v185
	v_mul_f32_e32 v0, v0, v186
	v_mul_f32_e32 v86, v86, v178
	ds_write2_b32 v139, v90, v0 offset0:128 offset1:160
	v_mul_f32_e32 v0, v74, v178
	v_mul_f32_e32 v86, v86, v185
	v_mul_f32_e32 v0, v0, v186
	v_mul_f32_e32 v85, v85, v181
	ds_write2_b32 v138, v86, v0 offset0:128 offset1:160
	v_mul_f32_e32 v0, v69, v181
	v_mul_f32_e32 v85, v185, v85
	v_mul_f32_e32 v0, v186, v0
	ds_write2_b32 v134, v85, v0 offset0:128 offset1:160
	v_mul_f32_e32 v0, v70, v38
	v_mul_f32_e32 v38, v55, v38
	s_waitcnt vmcnt(1)
	v_mul_f32_e32 v0, v0, v187
	s_waitcnt vmcnt(0)
	v_mul_f32_e32 v38, v38, v188
	v_mul_f32_e32 v68, v68, v167
	ds_write2_b32 v179, v0, v38 offset0:192 offset1:224
	v_mul_f32_e32 v0, v52, v167
	v_mul_f32_e32 v68, v68, v187
	v_mul_f32_e32 v0, v0, v188
	v_mul_f32_e32 v65, v65, v71
	ds_write2_b32 v151, v68, v0 offset0:192 offset1:224
	v_mul_f32_e32 v0, v49, v71
	v_mul_f32_e32 v65, v65, v187
	v_mul_f32_e32 v0, v0, v188
	v_mul_f32_e32 v64, v64, v39
	ds_write2_b32 v148, v65, v0 offset0:192 offset1:224
	v_mul_f32_e32 v0, v48, v39
	v_mul_f32_e32 v64, v64, v187
	v_mul_f32_e32 v0, v0, v188
	v_mul_f32_e32 v67, v67, v168
	ds_write2_b32 v145, v64, v0 offset0:192 offset1:224
	v_mul_f32_e32 v0, v51, v168
	v_mul_f32_e32 v67, v67, v187
	v_mul_f32_e32 v0, v0, v188
	v_mul_f32_e32 v66, v66, v169
	ds_write2_b32 v144, v67, v0 offset0:192 offset1:224
	v_mul_f32_e32 v0, v50, v169
	v_mul_f32_e32 v66, v66, v187
	v_mul_f32_e32 v0, v0, v188
	v_mul_f32_e32 v61, v61, v170
	ds_write2_b32 v146, v66, v0 offset0:192 offset1:224
	v_mul_f32_e32 v0, v45, v170
	v_mul_f32_e32 v61, v61, v187
	v_mul_f32_e32 v0, v0, v188
	v_mul_f32_e32 v60, v60, v171
	ds_write2_b32 v141, v61, v0 offset0:192 offset1:224
	v_mul_f32_e32 v0, v44, v171
	v_mul_f32_e32 v60, v60, v187
	v_mul_f32_e32 v0, v0, v188
	v_mul_f32_e32 v63, v63, v172
	ds_write2_b32 v140, v60, v0 offset0:192 offset1:224
	v_mul_f32_e32 v0, v47, v172
	v_mul_f32_e32 v63, v63, v187
	v_mul_f32_e32 v0, v0, v188
	v_mul_f32_e32 v62, v62, v173
	ds_write2_b32 v143, v63, v0 offset0:192 offset1:224
	v_mul_f32_e32 v0, v46, v173
	v_mul_f32_e32 v62, v62, v187
	v_mul_f32_e32 v0, v0, v188
	v_mul_f32_e32 v57, v57, v174
	ds_write2_b32 v142, v62, v0 offset0:192 offset1:224
	v_mul_f32_e32 v0, v41, v174
	v_mul_f32_e32 v57, v57, v187
	v_mul_f32_e32 v0, v0, v188
	v_mul_f32_e32 v56, v56, v175
	ds_write2_b32 v137, v57, v0 offset0:192 offset1:224
	v_mul_f32_e32 v0, v40, v175
	v_mul_f32_e32 v56, v56, v187
	v_mul_f32_e32 v0, v0, v188
	v_mul_f32_e32 v59, v59, v176
	ds_write2_b32 v136, v56, v0 offset0:192 offset1:224
	v_mul_f32_e32 v0, v43, v176
	v_mul_f32_e32 v59, v59, v187
	v_mul_f32_e32 v0, v0, v188
	v_mul_f32_e32 v58, v58, v177
	ds_write2_b32 v147, v59, v0 offset0:192 offset1:224
	v_mul_f32_e32 v0, v42, v177
	v_mul_f32_e32 v58, v58, v187
	v_mul_f32_e32 v0, v0, v188
	v_mul_f32_e32 v54, v54, v178
	ds_write2_b32 v139, v58, v0 offset0:192 offset1:224
	v_mul_f32_e32 v0, v37, v178
	v_mul_f32_e32 v54, v54, v187
	v_mul_f32_e32 v0, v0, v188
	v_mul_f32_e32 v53, v53, v181
	ds_write2_b32 v138, v54, v0 offset0:192 offset1:224
	v_mul_f32_e32 v0, v36, v181
	v_mul_f32_e32 v53, v53, v187
	v_mul_f32_e32 v0, v0, v188
	ds_write2_b32 v134, v53, v0 offset0:192 offset1:224
	s_branch .LBB0_256
